# phase Y: second-half NSA items claimed dynamically per XCC (heaviest first) instead of static pairing
# speedup vs baseline: 1.0313x; 1.0313x over previous
; __device__ void phase_y(const Params& p, int layer, unsigned char* smem) {
;   constexpr int NI = 8 * 2 * 64;
;   const int G = gridDim.x;
;   for (int i = blockIdx.x; i < NI / 2; i += G) {
; #pragma unroll 1
;     for (int h = 0; h < 2; ++h) {
;       int it = h ? (NI - 1 - i) : i;
;       int qt = 63 - (it >> 4); int r = it & 15; int b = r >> 1, g = r & 1;
;       item_nsa(p, layer, b, g, qt, smem);
;     }
;   }
; }
; __device__ void run_phase(const Params& p, int ph, unsigned char* smem) {
;   if (ph == 0) { phase_setup(p, smem); phase_rmsnorm<0>(p.x, p.norm_w, P_XN, nullptr); return; }
;   if (ph == NPH - 1) { phase_rmsnorm<1>(p.out, p.final_norm, nullptr, p.out); return; }
;   const int layer = (ph - 1) / 5, sub = (ph - 1) % 5;
;   switch (sub) {
;     case 0: phase_rmsnorm<0>(p.out, p.norm_w + layer * DM, P_XN, nullptr); break;
;     case 1: phase_inproj(p, layer, smem); break;
;     case 2: phase_x(p, layer, smem); break;
;     case 3: phase_y(p, layer, smem); break;
.LBB0_27:
	v_writelane_b32 v255, s52, 19
	s_add_i32 s0, s52, -1
	s_mul_hi_i32 s1, s0, 0x66666667
	s_lshr_b32 s6, s1, 31
	s_ashr_i32 s1, s1, 1
	s_add_i32 s8, s1, s6
	v_writelane_b32 v255, s53, 20
	s_mov_b32 s6, s8
	s_mul_i32 s1, s8, 5
	v_writelane_b32 v255, s6, 21
	s_sub_i32 s44, s0, s1
	s_mov_b64 s[0:1], -1
	v_writelane_b32 v255, s7, 22
	s_cmp_lt_i32 s44, 2
	s_mov_b64 s[70:71], 0
	s_cbranch_scc1 .LBB0_281
	s_cmp_gt_i32 s44, 2
	v_writelane_b32 v255, s44, 23
	s_cbranch_scc0 .LBB0_192
	s_cmp_eq_u32 s44, 3
	s_mov_b64 s[70:71], -1
	s_cbranch_scc0 .LBB0_191
	v_readlane_b32 s0, v254, 2
	v_readlane_b32 s1, v254, 3
	s_andn2_b64 vcc, exec, s[0:1]
	s_cbranch_vccnz .LBB0_190
	v_readlane_b32 s9, v253, 0
	v_readlane_b32 s0, v253, 3
	v_readlane_b32 s1, v253, 4
	s_load_dword s0, s[0:1], 0x0
	v_mov_b32_e32 v0, 0x12104
	ds_read_b32 v0, v0
	s_waitcnt lgkmcnt(0)
	v_readfirstlane_b32 s1, v0
	v_writelane_b32 v255, s87, 60
	s_cmpk_lg_u32 s0, 0x200
	s_cbranch_scc1 .LBB0_33
	s_cmpk_lg_u32 s1, 8
	s_cbranch_scc1 .LBB0_33
	s_mov_b32 s0, 1
	v_writelane_b32 v255, s0, 60
	s_getreg_b32 s0, hwreg(HW_REG_XCC_ID, 0, 4)
	v_writelane_b32 v255, s0, 57
	s_lshl_b32 s0, s0, 6
	v_readlane_b32 s1, v255, 21
	s_lshl_b32 s1, s1, 9
	s_add_i32 s0, s0, s1
	s_addk_i32 s0, 0x3800
	s_add_u32 s30, s88, s0
	s_addc_u32 s31, s89, 0
	v_writelane_b32 v255, s30, 58
	v_writelane_b32 v255, s31, 59
	v_cmp_eq_u32_e32 vcc, 0, v210
	s_and_saveexec_b64 s[38:39], vcc
	v_mov_b32_e32 v2, 1
	s_nop 4
	global_atomic_add v211, v1, v2, s[30:31] sc0
	s_or_b64 exec, exec, s[38:39]
	s_branch .LBB0_33

; __device__ __forceinline__ float bf2f(u16 b) { return __uint_as_float(((unsigned)b) << 16); }
; __device__ __forceinline__ float silu_f(float x) { return x * __builtin_amdgcn_rcpf(1.f + __expf(-x)); }
; __device__ void item_nsa(const Params& p, int layer, int b, int g, int qt, unsigned char* smem) {
;     ...
;     for (int i = 0; i < 4; ++i) {
;       const int c = tid + i * 256;
;       const int row = c >> 3, ch = c & 7;
;       gfin[i] = *(const u32x4*)(P_H + ((size_t)b * SEQ + q0 + (row & 31)) * HS + C_GC + (g * 4 + (row >> 5)) * 64 + ch * 8);
;     }
; #pragma unroll
;     for (int n = 0; n < 2; ++n) {
;       float inv = gate[n][1] / l[n];
; #pragma unroll
;       for (int dt = 0; dt < 4; ++dt) {
;         uint2 v = *(const uint2*)(sOf + n * 16 * 72 + dt * 16);
;         float a0 = bf2f((u16)(v.x & 0xffff)) + O[n][dt][0] * inv, a1 = bf2f((u16)(v.x >> 16)) + O[n][dt][1] * inv;
;         float a2 = bf2f((u16)(v.y & 0xffff)) + O[n][dt][2] * inv, a3 = bf2f((u16)(v.y >> 16)) + O[n][dt][3] * inv;
;         uint2 o; o.x = pack2(a0, a1); o.y = pack2(a2, a3);
;         *(uint2*)(sOf + n * 16 * 72 + dt * 16) = o;
;       }
;     }
;   }
;   __syncthreads();
;   {
;     const u16* sRow = (const u16*)sImp;
; #pragma unroll
;     for (int i = 0; i < 4; ++i) {
;       const int c = tid + i * 256;
;       const int row = c >> 3, ch = c & 7;
;       const size_t tok = (size_t)b * SEQ + q0 + (row & 31);
;       const int hcol = (g * 4 + (row >> 5)) * 64 + ch * 8;
;       u32x4 v = *(const u32x4*)(sRow + row * 72 + ch * 8);
;       u32x4 gt = gfin[i];
;       u32x4 o;
; #pragma unroll
;       for (int k = 0; k < 4; ++k) {
;         float x0 = bf2f((u16)(v[k] & 0xffff)) * silu_f(bf2f((u16)(gt[k] & 0xffff)));
;         float x1 = bf2f((u16)(v[k] >> 16)) * silu_f(bf2f((u16)(gt[k] >> 16)));
;         o[k] = pack2(x0, x1);
;       }
;       *(u32x4*)(P_XN + tok * DM + 512 + hcol) = o;
;     }
.LBB0_34:
	v_and_b32_e32 v0, 0xffff0000, v202
	v_mul_f32_e32 v0, 0xbfb8aa3b, v0
	v_exp_f32_e32 v0, v0
	s_lshl_b32 s0, s35, 11
	s_ashr_i32 s1, s8, 31
	s_add_u32 s0, s0, s8
	v_add_f32_e32 v0, 1.0, v0
	s_waitcnt vmcnt(1)
	v_rcp_f32_e32 v68, v0
	v_and_b32_e32 v0, 0xffff0000, v191
	v_mul_f32_e32 v0, 0xbfb8aa3b, v0
	v_exp_f32_e32 v0, v0
	v_mov_b64_e32 v[2:3], s[88:89]
	s_addc_u32 s1, 0, s1
	v_and_b32_e32 v37, 56, v193
	v_add_f32_e32 v0, 1.0, v0
	v_rcp_f32_e32 v62, v0
	v_lshrrev_b32_e32 v0, 3, v189
	v_and_or_b32 v0, v0, 31, s0
	v_mad_u64_u32 v[2:3], s[18:19], v0, s3, v[2:3]
	v_mad_i32_i24 v3, s1, v228, v3
	v_lshlrev_b32_e32 v0, 1, v37
	v_ashrrev_i32_e32 v4, 8, v189
	v_lshl_add_u64 v[2:3], v[2:3], 0, v[0:1]
	s_mov_b64 s[18:19], 0x4925c30
	v_add_lshl_u32 v60, s25, v4, 6
	v_lshl_add_u64 v[2:3], v[2:3], 0, s[18:19]
	v_ashrrev_i32_e32 v61, 31, v60
	v_lshl_add_u64 v[4:5], v[60:61], 1, v[2:3]
	global_load_dwordx4 v[14:17], v[4:5], off
	v_add_u32_e32 v61, 0x100, v189
	v_ashrrev_i32_e32 v4, 8, v61
	v_add_lshl_u32 v58, v4, s25, 6
	v_ashrrev_i32_e32 v59, 31, v58
	v_lshl_add_u64 v[4:5], v[58:59], 1, v[2:3]
	v_add_u32_e32 v57, 0x200, v189
	global_load_dwordx4 v[10:13], v[4:5], off
	v_ashrrev_i32_e32 v4, 8, v57
	v_add_lshl_u32 v38, v4, s25, 6
	v_ashrrev_i32_e32 v39, 31, v38
	v_lshl_add_u64 v[4:5], v[38:39], 1, v[2:3]
	v_add_u32_e32 v39, 0x300, v189
	global_load_dwordx4 v[6:9], v[4:5], off
	v_ashrrev_i32_e32 v4, 8, v39
	v_add_lshl_u32 v18, v4, s25, 6
	v_ashrrev_i32_e32 v19, 31, v18
	v_lshl_add_u64 v[2:3], v[18:19], 1, v[2:3]
	v_div_scale_f32 v19, s[18:19], v56, v56, v62
	v_rcp_f32_e32 v59, v19
	s_movk_i32 s8, 0x90
	global_load_dwordx4 v[2:5], v[2:3], off
	s_movk_i32 s15, 0x90
	v_fma_f32 v63, -v19, v59, 1.0
	v_fmac_f32_e32 v59, v63, v59
	v_div_scale_f32 v63, vcc, v62, v56, v62
	v_mul_f32_e32 v64, v63, v59
	v_fma_f32 v65, -v19, v64, v63
	v_fmac_f32_e32 v64, v65, v59
	v_fma_f32 v19, -v19, v64, v63
	v_div_fmas_f32 v19, v19, v59, v64
	v_div_fixup_f32 v56, v19, v56, v62
	ds_read2_b64 v[62:65], v151 offset1:4
	v_div_scale_f32 v19, s[18:19], v36, v36, v68
	s_waitcnt lgkmcnt(0)
	v_lshlrev_b32_e32 v66, 16, v62
	v_and_b32_e32 v67, 0xffff0000, v62
	v_lshlrev_b32_e32 v62, 16, v63
	v_and_b32_e32 v63, 0xffff0000, v63
	v_pk_fma_f32 v[52:53], v[52:53], v[56:57], v[66:67] op_sel_hi:[1,0,1]
	v_pk_fma_f32 v[54:55], v[54:55], v[56:57], v[62:63] op_sel_hi:[1,0,1]
	v_cvt_pk_bf16_f32 v52, v52, v53
	v_cvt_pk_bf16_f32 v53, v54, v55
	v_lshlrev_b32_e32 v54, 16, v64
	v_and_b32_e32 v55, 0xffff0000, v64
	v_pk_fma_f32 v[48:49], v[48:49], v[56:57], v[54:55] op_sel_hi:[1,0,1]
	v_lshlrev_b32_e32 v54, 16, v65
	v_and_b32_e32 v55, 0xffff0000, v65
	v_pk_fma_f32 v[50:51], v[50:51], v[56:57], v[54:55] op_sel_hi:[1,0,1]
	v_cvt_pk_bf16_f32 v48, v48, v49
	v_cvt_pk_bf16_f32 v49, v50, v51
	ds_write2_b64 v151, v[52:53], v[48:49] offset1:4
	ds_read2_b64 v[48:51], v151 offset0:8 offset1:12
	s_waitcnt lgkmcnt(0)
	v_lshlrev_b32_e32 v52, 16, v48
	v_and_b32_e32 v53, 0xffff0000, v48
	v_lshlrev_b32_e32 v48, 16, v49
	v_and_b32_e32 v49, 0xffff0000, v49
	v_pk_fma_f32 v[44:45], v[44:45], v[56:57], v[52:53] op_sel_hi:[1,0,1]
	v_pk_fma_f32 v[46:47], v[46:47], v[56:57], v[48:49] op_sel_hi:[1,0,1]
	v_cvt_pk_bf16_f32 v44, v44, v45
	v_cvt_pk_bf16_f32 v45, v46, v47
	v_lshlrev_b32_e32 v46, 16, v50
	v_and_b32_e32 v47, 0xffff0000, v50
	v_pk_fma_f32 v[40:41], v[40:41], v[56:57], v[46:47] op_sel_hi:[1,0,1]
	v_lshlrev_b32_e32 v46, 16, v51
	v_and_b32_e32 v47, 0xffff0000, v51
	v_pk_fma_f32 v[42:43], v[42:43], v[56:57], v[46:47] op_sel_hi:[1,0,1]
	v_cvt_pk_bf16_f32 v40, v40, v41
	v_cvt_pk_bf16_f32 v41, v42, v43
	ds_write2_b64 v151, v[44:45], v[40:41] offset0:8 offset1:12
	v_rcp_f32_e32 v40, v19
	s_nop 0
	v_fma_f32 v41, -v19, v40, 1.0
	v_fmac_f32_e32 v40, v41, v40
	v_div_scale_f32 v41, vcc, v68, v36, v68
	v_mul_f32_e32 v42, v41, v40
	v_fma_f32 v43, -v19, v42, v41
	v_fmac_f32_e32 v42, v43, v40
	v_fma_f32 v19, -v19, v42, v41
	v_div_fmas_f32 v19, v19, v40, v42
	ds_read2_b64 v[40:43], v150 offset0:32 offset1:36
	v_div_fixup_f32 v36, v19, v36, v68
	v_ashrrev_i32_e32 v19, 3, v189
	s_waitcnt lgkmcnt(0)
	v_lshlrev_b32_e32 v44, 16, v40
	v_and_b32_e32 v45, 0xffff0000, v40
	v_lshlrev_b32_e32 v40, 16, v41
	v_and_b32_e32 v41, 0xffff0000, v41
	v_pk_fma_f32 v[32:33], v[32:33], v[36:37], v[44:45] op_sel_hi:[1,0,1]
	v_pk_fma_f32 v[34:35], v[34:35], v[36:37], v[40:41] op_sel_hi:[1,0,1]
	v_cvt_pk_bf16_f32 v32, v32, v33
	v_cvt_pk_bf16_f32 v33, v34, v35
	v_lshlrev_b32_e32 v34, 16, v42
	v_and_b32_e32 v35, 0xffff0000, v42
	v_pk_fma_f32 v[28:29], v[28:29], v[36:37], v[34:35] op_sel_hi:[1,0,1]
	v_lshlrev_b32_e32 v34, 16, v43
	v_and_b32_e32 v35, 0xffff0000, v43
	v_pk_fma_f32 v[30:31], v[30:31], v[36:37], v[34:35] op_sel_hi:[1,0,1]
	v_cvt_pk_bf16_f32 v28, v28, v29
	v_cvt_pk_bf16_f32 v29, v30, v31
	ds_write2_b64 v150, v[32:33], v[28:29] offset0:32 offset1:36
	ds_read2_b64 v[28:31], v150 offset0:40 offset1:44
	s_waitcnt lgkmcnt(0)
	v_lshlrev_b32_e32 v32, 16, v28
	v_and_b32_e32 v33, 0xffff0000, v28
	v_lshlrev_b32_e32 v28, 16, v29
	v_and_b32_e32 v29, 0xffff0000, v29
	v_pk_fma_f32 v[24:25], v[24:25], v[36:37], v[32:33] op_sel_hi:[1,0,1]
	v_pk_fma_f32 v[26:27], v[26:27], v[36:37], v[28:29] op_sel_hi:[1,0,1]
	v_cvt_pk_bf16_f32 v24, v24, v25
	v_cvt_pk_bf16_f32 v25, v26, v27
	v_lshlrev_b32_e32 v26, 16, v30
	v_and_b32_e32 v27, 0xffff0000, v30
	v_pk_fma_f32 v[20:21], v[20:21], v[36:37], v[26:27] op_sel_hi:[1,0,1]
	v_lshlrev_b32_e32 v26, 16, v31
	v_and_b32_e32 v27, 0xffff0000, v31
	v_pk_fma_f32 v[22:23], v[22:23], v[36:37], v[26:27] op_sel_hi:[1,0,1]
	v_cvt_pk_bf16_f32 v20, v20, v21
	v_cvt_pk_bf16_f32 v21, v22, v23
	ds_write2_b64 v150, v[24:25], v[20:21] offset0:40 offset1:44
	s_waitcnt vmcnt(3)
	v_lshlrev_b32_e32 v24, 16, v14
	v_and_b32_e32 v25, 0xffff0000, v14
	v_mul_f32_e32 v14, 0xbfb8aa3b, v24
	v_exp_f32_e32 v14, v14
	v_mad_u64_u32 v[20:21], s[18:19], v19, s8, v[0:1]
	s_waitcnt lgkmcnt(0)
	v_add_f32_e32 v14, 1.0, v14
	v_rcp_f32_e32 v26, v14
	v_mul_f32_e32 v14, 0xbfb8aa3b, v25
	v_exp_f32_e32 v14, v14
	s_barrier
; __device__ __forceinline__ float bf2f(u16 b) { return __uint_as_float(((unsigned)b) << 16); }
; __device__ __forceinline__ float silu_f(float x) { return x * __builtin_amdgcn_rcpf(1.f + __expf(-x)); }
; __device__ void item_nsa(const Params& p, int layer, int b, int g, int qt, unsigned char* smem) {
;     ...
;   {
;     const u16* sRow = (const u16*)sImp;
; #pragma unroll
;     for (int i = 0; i < 4; ++i) {
;       const int c = tid + i * 256;
;       const int row = c >> 3, ch = c & 7;
;       const size_t tok = (size_t)b * SEQ + q0 + (row & 31);
;       const int hcol = (g * 4 + (row >> 5)) * 64 + ch * 8;
;       u32x4 v = *(const u32x4*)(sRow + row * 72 + ch * 8);
;       u32x4 gt = gfin[i];
;       u32x4 o;
; #pragma unroll
;       for (int k = 0; k < 4; ++k) {
;         float x0 = bf2f((u16)(v[k] & 0xffff)) * silu_f(bf2f((u16)(gt[k] & 0xffff)));
;         float x1 = bf2f((u16)(v[k] >> 16)) * silu_f(bf2f((u16)(gt[k] >> 16)));
;         o[k] = pack2(x0, x1);
;       }
;       *(u32x4*)(P_XN + tok * DM + 512 + hcol) = o;
;     }
	ds_read_b128 v[20:23], v20 offset:36864
	v_add_f32_e32 v14, 1.0, v14
	v_rcp_f32_e32 v27, v14
	s_waitcnt lgkmcnt(0)
	v_lshlrev_b32_e32 v28, 16, v20
	v_and_b32_e32 v29, 0xffff0000, v20
	v_pk_mul_f32 v[24:25], v[26:27], v[24:25]
	v_lshlrev_b32_e32 v26, 16, v21
	v_pk_mul_f32 v[24:25], v[24:25], v[28:29]
	v_and_b32_e32 v27, 0xffff0000, v21
	v_cvt_pk_bf16_f32 v14, v24, v25
	v_lshlrev_b32_e32 v24, 16, v15
	v_and_b32_e32 v25, 0xffff0000, v15
	v_mul_f32_e32 v15, 0xbfb8aa3b, v24
	v_exp_f32_e32 v15, v15
	s_nop 0
	v_add_f32_e32 v15, 1.0, v15
	v_rcp_f32_e32 v20, v15
	v_mul_f32_e32 v15, 0xbfb8aa3b, v25
	v_exp_f32_e32 v15, v15
	s_nop 0
	v_add_f32_e32 v15, 1.0, v15
	v_rcp_f32_e32 v21, v15
	s_nop 0
	v_pk_mul_f32 v[20:21], v[20:21], v[24:25]
	s_nop 0
	v_pk_mul_f32 v[20:21], v[20:21], v[26:27]
	v_lshlrev_b32_e32 v26, 16, v22
	v_cvt_pk_bf16_f32 v15, v20, v21
	v_lshlrev_b32_e32 v20, 16, v16
	v_and_b32_e32 v21, 0xffff0000, v16
	v_mul_f32_e32 v16, 0xbfb8aa3b, v20
	v_exp_f32_e32 v16, v16
	v_and_b32_e32 v27, 0xffff0000, v22
	v_add_f32_e32 v16, 1.0, v16
	v_rcp_f32_e32 v24, v16
	v_mul_f32_e32 v16, 0xbfb8aa3b, v21
	v_exp_f32_e32 v16, v16
	s_nop 0
	v_add_f32_e32 v16, 1.0, v16
	v_rcp_f32_e32 v25, v16
	s_nop 0
	v_pk_mul_f32 v[20:21], v[24:25], v[20:21]
	s_nop 0
	v_pk_mul_f32 v[20:21], v[20:21], v[26:27]
	v_lshlrev_b32_e32 v24, 16, v23
	v_cvt_pk_bf16_f32 v16, v20, v21
	v_lshlrev_b32_e32 v20, 16, v17
	v_and_b32_e32 v21, 0xffff0000, v17
	v_mul_f32_e32 v17, 0xbfb8aa3b, v20
	v_exp_f32_e32 v17, v17
	v_and_b32_e32 v25, 0xffff0000, v23
	v_add_f32_e32 v17, 1.0, v17
	v_rcp_f32_e32 v22, v17
	v_mul_f32_e32 v17, 0xbfb8aa3b, v21
	v_exp_f32_e32 v17, v17
	s_nop 0
	v_add_f32_e32 v17, 1.0, v17
	v_rcp_f32_e32 v23, v17
	s_nop 0
	v_pk_mul_f32 v[20:21], v[22:23], v[20:21]
	s_nop 0
	v_pk_mul_f32 v[20:21], v[20:21], v[24:25]
	v_or_b32_e32 v22, v60, v37
	v_cvt_pk_bf16_f32 v17, v20, v21
	v_and_or_b32 v20, v19, 31, s0
	v_mov_b32_e32 v21, s1
	v_lshlrev_b64 v[24:25], 11, v[20:21]
	v_lshl_add_u64 v[24:25], s[88:89], 0, v[24:25]
	v_ashrrev_i32_e32 v23, 31, v22
	v_lshl_add_u64 v[22:23], v[22:23], 1, v[24:25]
	s_mov_b32 s1, 0x2924000
	v_add_co_u32_e32 v22, vcc, s1, v22
	v_ashrrev_i32_e32 v19, 3, v61
	s_nop 0
	v_addc_co_u32_e32 v23, vcc, 0, v23, vcc
	global_store_dwordx4 v[22:23], v[14:17], off offset:2048
	s_waitcnt vmcnt(3)
	v_lshlrev_b32_e32 v22, 16, v10
	v_and_b32_e32 v23, 0xffff0000, v10
	v_mul_f32_e32 v10, 0xbfb8aa3b, v22
	v_exp_f32_e32 v10, v10
	v_mad_u64_u32 v[14:15], s[18:19], v19, s8, v[0:1]
	ds_read_b128 v[14:17], v14 offset:36864
	v_add_f32_e32 v10, 1.0, v10
	v_rcp_f32_e32 v24, v10
	v_mul_f32_e32 v10, 0xbfb8aa3b, v23
	v_exp_f32_e32 v10, v10
	s_waitcnt lgkmcnt(0)
	v_lshlrev_b32_e32 v26, 16, v14
	v_and_b32_e32 v27, 0xffff0000, v14
	v_and_or_b32 v20, v19, 31, s0
	v_add_f32_e32 v10, 1.0, v10
	v_rcp_f32_e32 v25, v10
	v_ashrrev_i32_e32 v19, 3, v57
	v_pk_mul_f32 v[22:23], v[24:25], v[22:23]
	s_nop 0
	v_pk_mul_f32 v[22:23], v[22:23], v[26:27]
	v_lshlrev_b32_e32 v24, 16, v15
	v_cvt_pk_bf16_f32 v10, v22, v23
	v_lshlrev_b32_e32 v22, 16, v11
	v_and_b32_e32 v23, 0xffff0000, v11
	v_mul_f32_e32 v11, 0xbfb8aa3b, v22
	v_exp_f32_e32 v11, v11
	v_and_b32_e32 v25, 0xffff0000, v15
	v_add_f32_e32 v11, 1.0, v11
	v_rcp_f32_e32 v14, v11
	v_mul_f32_e32 v11, 0xbfb8aa3b, v23
	v_exp_f32_e32 v11, v11
	s_nop 0
	v_add_f32_e32 v11, 1.0, v11
	v_rcp_f32_e32 v15, v11
	s_nop 0
	v_pk_mul_f32 v[14:15], v[14:15], v[22:23]
	s_nop 0
	v_pk_mul_f32 v[14:15], v[14:15], v[24:25]
	v_lshlrev_b32_e32 v24, 16, v16
	v_cvt_pk_bf16_f32 v11, v14, v15
	v_lshlrev_b32_e32 v14, 16, v12
	v_and_b32_e32 v15, 0xffff0000, v12
	v_mul_f32_e32 v12, 0xbfb8aa3b, v14
	v_exp_f32_e32 v12, v12
	v_and_b32_e32 v25, 0xffff0000, v16
	v_add_f32_e32 v12, 1.0, v12
	v_rcp_f32_e32 v22, v12
	v_mul_f32_e32 v12, 0xbfb8aa3b, v15
	v_exp_f32_e32 v12, v12
	s_nop 0
	v_add_f32_e32 v12, 1.0, v12
	v_rcp_f32_e32 v23, v12
	s_nop 0
	v_pk_mul_f32 v[14:15], v[22:23], v[14:15]
	s_nop 0
	v_pk_mul_f32 v[14:15], v[14:15], v[24:25]
	v_lshlrev_b32_e32 v22, 16, v17
	v_cvt_pk_bf16_f32 v12, v14, v15
	v_lshlrev_b32_e32 v14, 16, v13
	v_and_b32_e32 v15, 0xffff0000, v13
	v_mul_f32_e32 v13, 0xbfb8aa3b, v14
	v_exp_f32_e32 v13, v13
	v_and_b32_e32 v23, 0xffff0000, v17
	v_add_f32_e32 v13, 1.0, v13
	v_rcp_f32_e32 v16, v13
	v_mul_f32_e32 v13, 0xbfb8aa3b, v15
	v_exp_f32_e32 v13, v13
	s_nop 0
	v_add_f32_e32 v13, 1.0, v13
	v_rcp_f32_e32 v17, v13
	s_nop 0
	v_pk_mul_f32 v[14:15], v[16:17], v[14:15]
	s_nop 0
	v_pk_mul_f32 v[14:15], v[14:15], v[22:23]
	v_lshlrev_b64 v[16:17], 11, v[20:21]
	v_cvt_pk_bf16_f32 v13, v14, v15
	v_or_b32_e32 v14, v58, v37
	v_lshl_add_u64 v[16:17], s[88:89], 0, v[16:17]
	v_ashrrev_i32_e32 v15, 31, v14
	v_lshl_add_u64 v[14:15], v[14:15], 1, v[16:17]
	v_add_co_u32_e32 v14, vcc, s1, v14
	v_and_or_b32 v20, v19, 31, s0
	s_nop 0
	v_addc_co_u32_e32 v15, vcc, 0, v15, vcc
	global_store_dwordx4 v[14:15], v[10:13], off offset:2048
	s_waitcnt vmcnt(3)
; __device__ __forceinline__ float bf2f(u16 b) { return __uint_as_float(((unsigned)b) << 16); }
; __device__ __forceinline__ float silu_f(float x) { return x * __builtin_amdgcn_rcpf(1.f + __expf(-x)); }
; __device__ void item_nsa(const Params& p, int layer, int b, int g, int qt, unsigned char* smem) {
;     ...
;   {
;     const u16* sRow = (const u16*)sImp;
; #pragma unroll
;     for (int i = 0; i < 4; ++i) {
;       const int c = tid + i * 256;
;       const int row = c >> 3, ch = c & 7;
;       const size_t tok = (size_t)b * SEQ + q0 + (row & 31);
;       const int hcol = (g * 4 + (row >> 5)) * 64 + ch * 8;
;       u32x4 v = *(const u32x4*)(sRow + row * 72 + ch * 8);
;       u32x4 gt = gfin[i];
;       u32x4 o;
; #pragma unroll
;       for (int k = 0; k < 4; ++k) {
;         float x0 = bf2f((u16)(v[k] & 0xffff)) * silu_f(bf2f((u16)(gt[k] & 0xffff)));
;         float x1 = bf2f((u16)(v[k] >> 16)) * silu_f(bf2f((u16)(gt[k] >> 16)));
;         o[k] = pack2(x0, x1);
;       }
;       *(u32x4*)(P_XN + tok * DM + 512 + hcol) = o;
;     }
; __device__ void phase_y(const Params& p, int layer, unsigned char* smem) {
;     ...
;   for (int i = blockIdx.x; i < NI / 2; i += G) {
; #pragma unroll 1
;     for (int h = 0; h < 2; ++h) {
;       int it = h ? (NI - 1 - i) : i;
;       int qt = 63 - (it >> 4); int r = it & 15; int b = r >> 1, g = r & 1;
;       item_nsa(p, layer, b, g, qt, smem);
;     }
;   }
	v_lshlrev_b32_e32 v14, 16, v6
	v_and_b32_e32 v15, 0xffff0000, v6
	v_mul_f32_e32 v6, 0xbfb8aa3b, v14
	v_exp_f32_e32 v6, v6
	v_mad_u64_u32 v[10:11], s[18:19], v19, s8, v[0:1]
	ds_read_b128 v[10:13], v10 offset:36864
	v_add_f32_e32 v6, 1.0, v6
	v_rcp_f32_e32 v16, v6
	v_mul_f32_e32 v6, 0xbfb8aa3b, v15
	v_exp_f32_e32 v6, v6
	s_waitcnt lgkmcnt(0)
	v_lshlrev_b32_e32 v22, 16, v10
	v_and_b32_e32 v23, 0xffff0000, v10
	v_add_f32_e32 v6, 1.0, v6
	v_rcp_f32_e32 v17, v6
	s_nop 0
	v_pk_mul_f32 v[14:15], v[16:17], v[14:15]
	s_nop 0
	v_pk_mul_f32 v[14:15], v[14:15], v[22:23]
	v_lshlrev_b32_e32 v16, 16, v11
	v_cvt_pk_bf16_f32 v6, v14, v15
	v_lshlrev_b32_e32 v14, 16, v7
	v_and_b32_e32 v15, 0xffff0000, v7
	v_mul_f32_e32 v7, 0xbfb8aa3b, v14
	v_exp_f32_e32 v7, v7
	v_and_b32_e32 v17, 0xffff0000, v11
	v_add_f32_e32 v7, 1.0, v7
	v_rcp_f32_e32 v10, v7
	v_mul_f32_e32 v7, 0xbfb8aa3b, v15
	v_exp_f32_e32 v7, v7
	s_nop 0
	v_add_f32_e32 v7, 1.0, v7
	v_rcp_f32_e32 v11, v7
	s_nop 0
	v_pk_mul_f32 v[10:11], v[10:11], v[14:15]
	s_nop 0
	v_pk_mul_f32 v[10:11], v[10:11], v[16:17]
	v_lshlrev_b32_e32 v16, 16, v12
	v_cvt_pk_bf16_f32 v7, v10, v11
	v_lshlrev_b32_e32 v10, 16, v8
	v_and_b32_e32 v11, 0xffff0000, v8
	v_mul_f32_e32 v8, 0xbfb8aa3b, v10
	v_exp_f32_e32 v8, v8
	v_and_b32_e32 v17, 0xffff0000, v12
	v_add_f32_e32 v8, 1.0, v8
	v_rcp_f32_e32 v14, v8
	v_mul_f32_e32 v8, 0xbfb8aa3b, v11
	v_exp_f32_e32 v8, v8
	s_nop 0
	v_add_f32_e32 v8, 1.0, v8
	v_rcp_f32_e32 v15, v8
	s_nop 0
	v_pk_mul_f32 v[10:11], v[14:15], v[10:11]
	s_nop 0
	v_pk_mul_f32 v[10:11], v[10:11], v[16:17]
	v_lshlrev_b32_e32 v14, 16, v13
	v_cvt_pk_bf16_f32 v8, v10, v11
	v_lshlrev_b32_e32 v10, 16, v9
	v_and_b32_e32 v11, 0xffff0000, v9
	v_mul_f32_e32 v9, 0xbfb8aa3b, v10
	v_exp_f32_e32 v9, v9
	v_and_b32_e32 v15, 0xffff0000, v13
	v_ashrrev_i32_e32 v16, 3, v39
	v_add_f32_e32 v9, 1.0, v9
	v_rcp_f32_e32 v12, v9
	v_mul_f32_e32 v9, 0xbfb8aa3b, v11
	v_exp_f32_e32 v9, v9
	s_nop 0
	v_add_f32_e32 v9, 1.0, v9
	v_rcp_f32_e32 v13, v9
	s_nop 0
	v_pk_mul_f32 v[10:11], v[12:13], v[10:11]
	s_nop 0
	v_pk_mul_f32 v[10:11], v[10:11], v[14:15]
	v_lshlrev_b64 v[12:13], 11, v[20:21]
	v_cvt_pk_bf16_f32 v9, v10, v11
	v_or_b32_e32 v10, v38, v37
	v_lshl_add_u64 v[12:13], s[88:89], 0, v[12:13]
	v_ashrrev_i32_e32 v11, 31, v10
	v_lshl_add_u64 v[10:11], v[10:11], 1, v[12:13]
	v_add_co_u32_e32 v10, vcc, s1, v10
	v_and_or_b32 v20, v16, 31, s0
	s_nop 0
	v_addc_co_u32_e32 v11, vcc, 0, v11, vcc
	global_store_dwordx4 v[10:11], v[6:9], off offset:2048
	s_waitcnt vmcnt(3)
	v_lshlrev_b32_e32 v10, 16, v2
	v_and_b32_e32 v11, 0xffff0000, v2
	v_mad_u64_u32 v[6:7], s[18:19], v16, s8, v[0:1]
	v_mul_f32_e32 v0, 0xbfb8aa3b, v10
	v_exp_f32_e32 v0, v0
	ds_read_b128 v[6:9], v6 offset:36864
	s_mov_b64 s[0:1], 0
	v_add_f32_e32 v0, 1.0, v0
	v_rcp_f32_e32 v12, v0
	v_mul_f32_e32 v0, 0xbfb8aa3b, v11
	v_exp_f32_e32 v0, v0
	s_waitcnt lgkmcnt(0)
	v_lshlrev_b32_e32 v14, 16, v6
	v_and_b32_e32 v15, 0xffff0000, v6
	v_add_f32_e32 v0, 1.0, v0
	v_rcp_f32_e32 v13, v0
	s_nop 0
	v_pk_mul_f32 v[10:11], v[12:13], v[10:11]
	s_nop 0
	v_pk_mul_f32 v[10:11], v[10:11], v[14:15]
	v_lshlrev_b32_e32 v12, 16, v7
	v_cvt_pk_bf16_f32 v2, v10, v11
	v_lshlrev_b32_e32 v10, 16, v3
	v_mul_f32_e32 v0, 0xbfb8aa3b, v10
	v_exp_f32_e32 v0, v0
	v_and_b32_e32 v11, 0xffff0000, v3
	v_and_b32_e32 v13, 0xffff0000, v7
	v_add_f32_e32 v0, 1.0, v0
	v_rcp_f32_e32 v6, v0
	v_mul_f32_e32 v0, 0xbfb8aa3b, v11
	v_exp_f32_e32 v0, v0
	s_nop 0
	v_add_f32_e32 v0, 1.0, v0
	v_rcp_f32_e32 v7, v0
	s_nop 0
	v_pk_mul_f32 v[6:7], v[6:7], v[10:11]
	s_nop 0
	v_pk_mul_f32 v[6:7], v[6:7], v[12:13]
	v_lshlrev_b32_e32 v12, 16, v8
	v_cvt_pk_bf16_f32 v3, v6, v7
	v_lshlrev_b32_e32 v6, 16, v4
	v_mul_f32_e32 v0, 0xbfb8aa3b, v6
	v_exp_f32_e32 v0, v0
	v_and_b32_e32 v7, 0xffff0000, v4
	v_and_b32_e32 v13, 0xffff0000, v8
	v_add_f32_e32 v0, 1.0, v0
	v_rcp_f32_e32 v10, v0
	v_mul_f32_e32 v0, 0xbfb8aa3b, v7
	v_exp_f32_e32 v0, v0
	s_nop 0
	v_add_f32_e32 v0, 1.0, v0
	v_rcp_f32_e32 v11, v0
	s_nop 0
	v_pk_mul_f32 v[6:7], v[10:11], v[6:7]
	s_nop 0
	v_pk_mul_f32 v[6:7], v[6:7], v[12:13]
	v_lshlrev_b32_e32 v10, 16, v9
	v_cvt_pk_bf16_f32 v4, v6, v7
	v_lshlrev_b32_e32 v6, 16, v5
	v_mul_f32_e32 v0, 0xbfb8aa3b, v6
	v_exp_f32_e32 v0, v0
	v_and_b32_e32 v7, 0xffff0000, v5
	v_and_b32_e32 v11, 0xffff0000, v9
	v_add_f32_e32 v0, 1.0, v0
	v_rcp_f32_e32 v8, v0
	v_mul_f32_e32 v0, 0xbfb8aa3b, v7
	v_exp_f32_e32 v0, v0
	s_nop 0
	v_add_f32_e32 v0, 1.0, v0
	v_rcp_f32_e32 v9, v0
	s_nop 0
	v_pk_mul_f32 v[6:7], v[8:9], v[6:7]
	s_nop 0
	v_pk_mul_f32 v[6:7], v[6:7], v[10:11]
	v_lshlrev_b64 v[8:9], 11, v[20:21]
	v_cvt_pk_bf16_f32 v5, v6, v7
	v_or_b32_e32 v6, v18, v37
	v_lshl_add_u64 v[8:9], s[88:89], 0, v[8:9]
	v_ashrrev_i32_e32 v7, 31, v6
	v_lshl_add_u64 v[6:7], v[6:7], 1, v[8:9]
	v_add_co_u32_e32 v6, vcc, 0x2924000, v6
	s_nop 1
	v_addc_co_u32_e32 v7, vcc, 0, v7, vcc
	s_and_b64 vcc, exec, s[6:7]
	global_store_dwordx4 v[6:7], v[2:5], off offset:2048
	v_readlane_b32 s38, v255, 60
	s_cmp_lg_u32 s38, 0
	s_cbranch_scc1 .Lnsa_next
	s_cbranch_vccnz .LBB0_32

; __device__ void phase_y(const Params& p, int layer, unsigned char* smem) {
;     ...
;   for (int i = blockIdx.x; i < NI / 2; i += G) {
; #pragma unroll 1
;     for (int h = 0; h < 2; ++h) {
;       int it = h ? (NI - 1 - i) : i;
;       int qt = 63 - (it >> 4); int r = it & 15; int b = r >> 1, g = r & 1;
;       item_nsa(p, layer, b, g, qt, smem);
;     }
;   }
.Lnsa_next:
	v_cmp_eq_u32_e32 vcc, 0, v210
	s_and_saveexec_b64 s[38:39], vcc
	s_cbranch_execz .Lnsa_n1
	s_waitcnt vmcnt(0)
	v_mov_b32_e32 v0, 0x13110
	ds_write_b32 v0, v211
	v_readlane_b32 s30, v255, 58
	v_readlane_b32 s31, v255, 59
	v_mov_b32_e32 v2, 1
	s_nop 4
	global_atomic_add v211, v1, v2, s[30:31] sc0
	s_waitcnt lgkmcnt(0)
.Lnsa_n1:
	s_or_b64 exec, exec, s[38:39]
	s_barrier
	v_mov_b32_e32 v0, 0x13110
	ds_read_b32 v0, v0
	s_waitcnt lgkmcnt(0)
	v_readfirstlane_b32 s38, v0
	s_cmp_gt_u32 s38, 63
	s_cbranch_scc1 .LBB0_190
	v_readlane_b32 s39, v255, 57
	s_lshl_b32 s38, s38, 3
	s_add_i32 s38, s38, s39
	s_addk_i32 s38, 0x200
	v_writelane_b32 v255, s38, 24
	s_mov_b64 s[0:1], 0
	s_branch .LBB0_35
.LBB0_190:
	s_waitcnt vmcnt(0)
	v_mov_b32_e32 v211, 0x358637bd
	s_mov_b64 s[70:71], 0
	s_movk_i32 s74, 0x3fff

; __global__ void __launch_bounds__(256, 2) hybrid_megakernel(Params p, int ph_lo, int ph_hi) {
;   __shared__ __attribute__((aligned(16))) unsigned char smem[SM_TOTAL];
;   __shared__ uint4 xb_words;
	.amdhsa_kernel _Z17hybrid_megakernel6Paramsii
		.amdhsa_group_segment_fixed_size 78112
		.amdhsa_private_segment_fixed_size 0
		.amdhsa_kernarg_size 416
		.amdhsa_user_sgpr_count 2
		.amdhsa_user_sgpr_dispatch_ptr 0
		.amdhsa_user_sgpr_queue_ptr 0
		.amdhsa_user_sgpr_kernarg_segment_ptr 1
		.amdhsa_user_sgpr_dispatch_id 0
		.amdhsa_user_sgpr_kernarg_preload_length 0
		.amdhsa_user_sgpr_kernarg_preload_offset 0
		.amdhsa_user_sgpr_private_segment_size 0
		.amdhsa_uses_dynamic_stack 0
		.amdhsa_enable_private_segment 0
		.amdhsa_system_sgpr_workgroup_id_x 1
		.amdhsa_system_sgpr_workgroup_id_y 0
		.amdhsa_system_sgpr_workgroup_id_z 0
		.amdhsa_system_sgpr_workgroup_info 0
		.amdhsa_system_vgpr_workitem_id 2
		.amdhsa_next_free_vgpr 256
		.amdhsa_next_free_sgpr 100
		.amdhsa_accum_offset 256
		.amdhsa_reserve_vcc 1
		.amdhsa_float_round_mode_32 0
		.amdhsa_float_round_mode_16_64 0
		.amdhsa_float_denorm_mode_32 3
		.amdhsa_float_denorm_mode_16_64 3
		.amdhsa_dx10_clamp 1
		.amdhsa_ieee_mode 1
		.amdhsa_fp16_overflow 0
		.amdhsa_tg_split 0
		.amdhsa_exception_fp_ieee_invalid_op 0
		.amdhsa_exception_fp_denorm_src 0
		.amdhsa_exception_fp_ieee_div_zero 0
		.amdhsa_exception_fp_ieee_overflow 0
		.amdhsa_exception_fp_ieee_underflow 0
		.amdhsa_exception_fp_ieee_inexact 0
		.amdhsa_exception_int_div_zero 0
	.end_amdhsa_kernel

; __global__ void __launch_bounds__(256, 2) hybrid_megakernel(Params p, int ph_lo, int ph_hi) {
;   __shared__ __attribute__((aligned(16))) unsigned char smem[SM_TOTAL];
;   __shared__ uint4 xb_words;
amdhsa.kernels:
  - .agpr_count:     0
    .args:
      - .offset:         0
        .size:           152
        .value_kind:     by_value
      - .offset:         152
        .size:           4
        .value_kind:     by_value
      - .offset:         156
        .size:           4
        .value_kind:     by_value
      - .offset:         160
        .size:           4
        .value_kind:     hidden_block_count_x
      - .offset:         164
        .size:           4
        .value_kind:     hidden_block_count_y
      - .offset:         168
        .size:           4
        .value_kind:     hidden_block_count_z
      - .offset:         172
        .size:           2
        .value_kind:     hidden_group_size_x
      - .offset:         174
        .size:           2
        .value_kind:     hidden_group_size_y
      - .offset:         176
        .size:           2
        .value_kind:     hidden_group_size_z
      - .offset:         178
        .size:           2
        .value_kind:     hidden_remainder_x
      - .offset:         180
        .size:           2
        .value_kind:     hidden_remainder_y
      - .offset:         182
        .size:           2
        .value_kind:     hidden_remainder_z
      - .offset:         200
        .size:           8
        .value_kind:     hidden_global_offset_x
      - .offset:         208
        .size:           8
        .value_kind:     hidden_global_offset_y
      - .offset:         216
        .size:           8
        .value_kind:     hidden_global_offset_z
      - .offset:         224
        .size:           2
        .value_kind:     hidden_grid_dims
      - .offset:         248
        .size:           8
        .value_kind:     hidden_multigrid_sync_arg
    .group_segment_fixed_size: 78112
    .kernarg_segment_align: 8
    .kernarg_segment_size: 416
    .language:       OpenCL C
    .language_version:
      - 2
      - 0
    .max_flat_workgroup_size: 256
    .name:           _Z17hybrid_megakernel6Paramsii
    .private_segment_fixed_size: 0
    .sgpr_count:     106
    .sgpr_spill_count: 159
    .symbol:         _Z17hybrid_megakernel6Paramsii.kd
    .uniform_work_group_size: 1
    .uses_dynamic_stack: false
    .vgpr_count:     256
    .vgpr_spill_count: 0
    .wavefront_size: 64
